# DIFF flash loop fast path: first value block's PV MFMAs issued inside the exp block as soon as each P fragment is final (MFMA shadow filled with softmax VALU)
# baseline (speedup 1.0000x reference)
.LBB0_494:
	s_andn2_saveexec_b64 s[0:1], s[0:1]
	s_cbranch_execz .LBB0_496
	s_or_b64 exec, exec, s[0:1]
	v_sub_f32_e32 v33, v201, v247
	v_fmamk_f32 v2, v114, 0x3e38aa3b, v33
	v_exp_f32_e32 v2, v2
	v_fmamk_f32 v3, v115, 0x3e38aa3b, v33
	v_exp_f32_e32 v3, v3
	v_fmamk_f32 v4, v116, 0x3e38aa3b, v33
	v_exp_f32_e32 v4, v4
	v_add_f32_e32 v5, 0, v2
	v_add_f32_e32 v5, v3, v5
	v_fmamk_f32 v6, v118, 0x3e38aa3b, v33
	v_add_f32_e32 v9, v4, v5
	v_fmamk_f32 v5, v117, 0x3e38aa3b, v33
	v_exp_f32_e32 v5, v5
	v_exp_f32_e32 v6, v6
	v_fmamk_f32 v7, v119, 0x3e38aa3b, v33
	v_exp_f32_e32 v7, v7
	v_fmamk_f32 v8, v120, 0x3e38aa3b, v33
	v_exp_f32_e32 v8, v8
	v_add_f32_e32 v9, v5, v9
	v_add_f32_e32 v9, v6, v9
	v_add_f32_e32 v9, v7, v9
	v_add_f32_e32 v13, v8, v9
	v_fmamk_f32 v9, v121, 0x3e38aa3b, v33
	v_exp_f32_e32 v9, v9
	v_cvt_pk_bf16_f32 v2, v2, v3
	v_cvt_pk_bf16_f32 v3, v4, v5
	v_cvt_pk_bf16_f32 v4, v6, v7
	v_cvt_pk_bf16_f32 v5, v8, v9
	v_fmamk_f32 v10, v122, 0x3e38aa3b, v33
	v_exp_f32_e32 v10, v10
	v_mfma_f32_32x32x16_bf16 v[82:97], v[182:185], v[2:5], v[82:97]
	v_fmamk_f32 v11, v123, 0x3e38aa3b, v33
	v_exp_f32_e32 v11, v11
	v_fmamk_f32 v12, v124, 0x3e38aa3b, v33
	v_exp_f32_e32 v12, v12
	v_add_f32_e32 v13, v9, v13
	v_add_f32_e32 v13, v10, v13
	v_add_f32_e32 v13, v11, v13
	v_add_f32_e32 v17, v12, v13
	v_fmamk_f32 v13, v125, 0x3e38aa3b, v33
	v_exp_f32_e32 v13, v13
	v_fmamk_f32 v14, v126, 0x3e38aa3b, v33
	v_exp_f32_e32 v14, v14
	v_fmamk_f32 v15, v127, 0x3e38aa3b, v33
	v_exp_f32_e32 v15, v15
	v_fmamk_f32 v16, v128, 0x3e38aa3b, v33
	v_exp_f32_e32 v16, v16
	v_add_f32_e32 v17, v13, v17
	v_add_f32_e32 v17, v14, v17
	v_add_f32_e32 v17, v15, v17
	v_add_f32_e32 v21, v16, v17
	v_fmamk_f32 v17, v129, 0x3e38aa3b, v33
	v_exp_f32_e32 v17, v17
	v_cvt_pk_bf16_f32 v6, v10, v11
	v_cvt_pk_bf16_f32 v7, v12, v13
	v_cvt_pk_bf16_f32 v8, v14, v15
	v_cvt_pk_bf16_f32 v9, v16, v17
	v_fmamk_f32 v18, v98, 0x3e38aa3b, v33
	v_exp_f32_e32 v18, v18
	v_mfma_f32_32x32x16_bf16 v[82:97], v[178:181], v[6:9], v[82:97]
	v_fmamk_f32 v19, v99, 0x3e38aa3b, v33
	v_exp_f32_e32 v19, v19
	v_fmamk_f32 v20, v100, 0x3e38aa3b, v33
	v_exp_f32_e32 v20, v20
	v_add_f32_e32 v21, v17, v21
	v_add_f32_e32 v21, v18, v21
	v_add_f32_e32 v21, v19, v21
	v_add_f32_e32 v25, v20, v21
	v_fmamk_f32 v21, v101, 0x3e38aa3b, v33
	v_exp_f32_e32 v21, v21
	v_fmamk_f32 v22, v102, 0x3e38aa3b, v33
	v_exp_f32_e32 v22, v22
	v_fmamk_f32 v23, v103, 0x3e38aa3b, v33
	v_exp_f32_e32 v23, v23
	v_fmamk_f32 v24, v104, 0x3e38aa3b, v33
	v_exp_f32_e32 v24, v24
	v_add_f32_e32 v25, v21, v25
	v_add_f32_e32 v25, v22, v25
	v_add_f32_e32 v25, v23, v25
	v_add_f32_e32 v29, v24, v25
	v_fmamk_f32 v25, v105, 0x3e38aa3b, v33
	v_exp_f32_e32 v25, v25
	v_cvt_pk_bf16_f32 v10, v18, v19
	v_cvt_pk_bf16_f32 v11, v20, v21
	v_cvt_pk_bf16_f32 v12, v22, v23
	v_cvt_pk_bf16_f32 v13, v24, v25
	v_fmamk_f32 v26, v106, 0x3e38aa3b, v33
	v_exp_f32_e32 v26, v26
	v_mfma_f32_32x32x16_bf16 v[82:97], v[174:177], v[10:13], v[82:97]
	v_fmamk_f32 v27, v107, 0x3e38aa3b, v33
	v_exp_f32_e32 v27, v27
	v_fmamk_f32 v28, v108, 0x3e38aa3b, v33
	v_exp_f32_e32 v28, v28
	v_add_f32_e32 v29, v25, v29
	v_add_f32_e32 v29, v26, v29
	v_add_f32_e32 v29, v27, v29
	v_add_f32_e32 v98, v28, v29
	v_fmamk_f32 v29, v109, 0x3e38aa3b, v33
	v_exp_f32_e32 v29, v29
	v_fmamk_f32 v30, v110, 0x3e38aa3b, v33
	v_exp_f32_e32 v30, v30
	v_fmamk_f32 v31, v111, 0x3e38aa3b, v33
	v_exp_f32_e32 v31, v31
	v_fmamk_f32 v32, v112, 0x3e38aa3b, v33
	v_exp_f32_e32 v32, v32
	v_add_f32_e32 v98, v29, v98
	v_add_f32_e32 v98, v30, v98
	v_add_f32_e32 v98, v31, v98
	v_add_f32_e32 v248, v32, v98
	v_fmac_f32_e32 v33, 0x3e38aa3b, v113
	v_exp_f32_e32 v33, v33
	v_cvt_pk_bf16_f32 v14, v26, v27
	v_cvt_pk_bf16_f32 v15, v28, v29
	v_cvt_pk_bf16_f32 v16, v30, v31
	v_cvt_pk_bf16_f32 v17, v32, v33
	v_add_u32_e32 v30, 0x5800, v226
	v_add_f32_e32 v98, v33, v248
	ds_read2_b64 v[18:21], v30 offset0:32 offset1:34
	ds_read2_b64 v[22:25], v30 offset0:36 offset1:38
	ds_read2_b64 v[26:29], v30 offset0:40 offset1:42
	ds_read2_b64 v[30:33], v30 offset0:44 offset1:46
	v_mfma_f32_32x32x16_bf16 v[82:97], v[170:173], v[14:17], v[82:97]
	v_add_f32_e32 v203, v203, v98
	s_branch .Lpv1_diff

.Lpv1_diff:
	s_waitcnt lgkmcnt(3)
	v_mfma_f32_32x32x16_bf16 v[66:81], v[18:21], v[2:5], v[66:81]
	s_waitcnt lgkmcnt(2)
	v_mfma_f32_32x32x16_bf16 v[66:81], v[22:25], v[6:9], v[66:81]
	s_waitcnt lgkmcnt(1)
	v_mfma_f32_32x32x16_bf16 v[66:81], v[26:29], v[10:13], v[66:81]
	s_waitcnt lgkmcnt(0)
	v_mfma_f32_32x32x16_bf16 v[66:81], v[30:33], v[14:17], v[66:81]
	v_add_u32_e32 v30, 0x6800, v226
	ds_read2_b64 v[18:21], v30 offset0:64 offset1:66
	ds_read2_b64 v[22:25], v30 offset0:68 offset1:70
	ds_read2_b64 v[26:29], v30 offset0:72 offset1:74
	ds_read2_b64 v[30:33], v30 offset0:76 offset1:78
	s_waitcnt lgkmcnt(3)
	v_mfma_f32_32x32x16_bf16 v[50:65], v[18:21], v[2:5], v[50:65]
	s_waitcnt lgkmcnt(2)
	v_mfma_f32_32x32x16_bf16 v[50:65], v[22:25], v[6:9], v[50:65]
	s_waitcnt lgkmcnt(1)
	v_mfma_f32_32x32x16_bf16 v[50:65], v[26:29], v[10:13], v[50:65]
	s_waitcnt lgkmcnt(0)
	v_mfma_f32_32x32x16_bf16 v[50:65], v[30:33], v[14:17], v[50:65]
	v_add_u32_e32 v30, 0x7800, v226
	ds_read2_b64 v[18:21], v30 offset0:96 offset1:98
	ds_read2_b64 v[22:25], v30 offset0:100 offset1:102
	ds_read2_b64 v[26:29], v30 offset0:104 offset1:106
	ds_read2_b64 v[30:33], v30 offset0:108 offset1:110
	s_waitcnt lgkmcnt(3)
	v_mfma_f32_32x32x16_bf16 v[34:49], v[18:21], v[2:5], v[34:49]
	s_and_b64 s[0:1], s[22:23], exec
	s_waitcnt lgkmcnt(2)
	v_mfma_f32_32x32x16_bf16 v[34:49], v[22:25], v[6:9], v[34:49]
	s_waitcnt lgkmcnt(1)
	v_mfma_f32_32x32x16_bf16 v[34:49], v[26:29], v[10:13], v[34:49]
	s_waitcnt lgkmcnt(0)
	v_mfma_f32_32x32x16_bf16 v[34:49], v[30:33], v[14:17], v[34:49]
	s_andn2_saveexec_b64 s[24:25], s[24:25]
	s_cbranch_execz .LBB0_482
